# conv items re-dealt: the 120 workgroups with four 192-key units plus a sample unit take none, the other 136 take two each
# baseline (speedup 1.0000x reference)
.LBB0_402:
	s_cmp_lg_u32 s0, s33
	s_mov_b64 s[0:1], -1
	s_cbranch_scc0 .LBB0_405
	v_readlane_b32 s0, v254, 14
	v_readlane_b32 s1, v254, 15
	s_andn2_b64 vcc, exec, s[0:1]
	s_waitcnt vmcnt(1)
	v_mov_b32_e32 v80, v159
	v_readlane_b32 s3, v254, 13
	s_cmpk_lg_i32 s34, 0x100
	s_cbranch_scc1 .Lconv_enter
	s_sub_i32 s10, s2, 8
	s_cmpk_lt_u32 s10, 0x78
	s_cbranch_scc1 .LBB0_404
	s_add_i32 s11, s2, 0xffffff88
	s_cmpk_lt_u32 s2, 8
	s_cselect_b32 s11, s2, s11
	s_sub_i32 s10, s11, s3
	s_lshl_b32 s10, s10, 6
	v_add_u32_e32 v80, s10, v80
	s_mov_b32 s3, s11
.Lconv_enter:
	s_cbranch_vccz .LBB0_411

.Lconv_rebal:
	s_addk_i32 s3, 0x88
	s_cmpk_lt_i32 s3, 0x110
	v_add_u32_e32 v80, 0x2200, v80
	s_cbranch_scc0 .LBB0_404
